# code placement: GEMM K-loop head padded onto a 64-byte boundary (5 s_nop executed once per tile before the loop)
# speedup vs baseline: 1.0048x; 1.0048x over previous
; template <class Epi, class Sched, bool ALIGN_EPI = false, bool SP2 = false>
; __device__ __forceinline__ void gemm_phase(PG8_LAS unsigned char* lds, const Gemm g, const Sched& S, const Epi& E, const int tid_in) {
;     ...
;         const char* nA = has_next ? (const char*)g.A + (size_t)nxt.pm * tstepA : cA; const char* nB = has_next ? (const char*)g.Bt + (size_t)nxt.pn * tstep : cB;
;         for (int t = 0; t < nt; t += 2) {
;             const bool last = (t == nt - 2);
;             const char* a1 = cA + (size_t)(t + 1) * kstep;
;             const char* a2 = last ? nA : cA + (size_t)(t + 2) * kstep; const char* b2 = last ? nB : cB + (size_t)(t + 2) * kstep;
;     ...
; #pragma unroll
;         for (int a = 0; a < 2; ++a)
; #pragma unroll
;             for (int b = 0; b < 2; ++b)
; #pragma unroll
;                 for (int m = 0; m < 4; ++m)
; #pragma unroll
;                     for (int n = 0; n < 2; ++n) acc[a][b][m][n] = (f32x4){0.f, 0.f, 0.f, 0.f};
;         cur = nxt; cA = nA; cB = nB; ++ui;
.LBB0_225:
	s_add_u32 vcc_lo, s48, 0x100
	s_addc_u32 vcc_hi, s49, 0
	s_add_u32 s46, s50, 0x80
	v_mov_b32_e32 v2, 0
	s_addc_u32 s47, s51, 0
	s_mov_b32 s48, 0
	v_mov_b32_e32 v3, v2
	v_mov_b32_e32 v4, v2
	v_mov_b32_e32 v5, v2
	v_mov_b32_e32 v6, v2
	v_mov_b32_e32 v7, v2
	v_mov_b32_e32 v8, v2
	v_mov_b32_e32 v9, v2
	v_mov_b32_e32 v18, v2
	v_mov_b32_e32 v19, v2
	v_mov_b32_e32 v20, v2
	v_mov_b32_e32 v21, v2
	v_mov_b32_e32 v22, v2
	v_mov_b32_e32 v23, v2
	v_mov_b32_e32 v24, v2
	v_mov_b32_e32 v25, v2
	v_mov_b32_e32 v34, v2
	v_mov_b32_e32 v35, v2
	v_mov_b32_e32 v36, v2
	v_mov_b32_e32 v37, v2
	v_mov_b32_e32 v38, v2
	v_mov_b32_e32 v39, v2
	v_mov_b32_e32 v40, v2
	v_mov_b32_e32 v41, v2
	v_mov_b32_e32 v50, v2
	v_mov_b32_e32 v51, v2
	v_mov_b32_e32 v52, v2
	v_mov_b32_e32 v53, v2
	v_mov_b32_e32 v54, v2
	v_mov_b32_e32 v55, v2
	v_mov_b32_e32 v56, v2
	v_mov_b32_e32 v57, v2
	v_mov_b32_e32 v10, v2
	v_mov_b32_e32 v11, v2
	v_mov_b32_e32 v12, v2
	v_mov_b32_e32 v13, v2
	v_mov_b32_e32 v14, v2
	v_mov_b32_e32 v15, v2
	v_mov_b32_e32 v16, v2
	v_mov_b32_e32 v17, v2
	v_mov_b32_e32 v26, v2
	v_mov_b32_e32 v27, v2
	v_mov_b32_e32 v28, v2
	v_mov_b32_e32 v29, v2
	v_mov_b32_e32 v30, v2
	v_mov_b32_e32 v31, v2
	v_mov_b32_e32 v32, v2
	v_mov_b32_e32 v33, v2
	v_mov_b32_e32 v42, v2
	v_mov_b32_e32 v43, v2
	v_mov_b32_e32 v44, v2
	v_mov_b32_e32 v45, v2
	v_mov_b32_e32 v46, v2
	v_mov_b32_e32 v47, v2
	v_mov_b32_e32 v48, v2
	v_mov_b32_e32 v49, v2
	v_mov_b32_e32 v58, v2
	v_mov_b32_e32 v59, v2
	v_mov_b32_e32 v60, v2
	v_mov_b32_e32 v61, v2
	v_mov_b32_e32 v62, v2
	v_mov_b32_e32 v63, v2
	v_mov_b32_e32 v64, v2
	v_mov_b32_e32 v65, v2
	v_mov_b32_e32 v66, v2
	v_mov_b32_e32 v67, v2
	v_mov_b32_e32 v68, v2
	v_mov_b32_e32 v69, v2
	v_mov_b32_e32 v70, v2
	v_mov_b32_e32 v71, v2
	v_mov_b32_e32 v72, v2
	v_mov_b32_e32 v73, v2
	v_mov_b32_e32 v82, v2
	v_mov_b32_e32 v83, v2
	v_mov_b32_e32 v84, v2
	v_mov_b32_e32 v85, v2
	v_mov_b32_e32 v86, v2
	v_mov_b32_e32 v87, v2
	v_mov_b32_e32 v88, v2
	v_mov_b32_e32 v89, v2
	v_mov_b32_e32 v98, v2
	v_mov_b32_e32 v99, v2
	v_mov_b32_e32 v100, v2
	v_mov_b32_e32 v101, v2
	v_mov_b32_e32 v102, v2
	v_mov_b32_e32 v103, v2
	v_mov_b32_e32 v104, v2
	v_mov_b32_e32 v105, v2
	v_mov_b32_e32 v114, v2
	v_mov_b32_e32 v115, v2
	v_mov_b32_e32 v116, v2
	v_mov_b32_e32 v117, v2
	v_mov_b32_e32 v118, v2
	v_mov_b32_e32 v119, v2
	v_mov_b32_e32 v120, v2
	v_mov_b32_e32 v121, v2
	v_mov_b32_e32 v74, v2
	v_mov_b32_e32 v75, v2
	v_mov_b32_e32 v76, v2
	v_mov_b32_e32 v77, v2
	v_mov_b32_e32 v78, v2
	v_mov_b32_e32 v79, v2
	v_mov_b32_e32 v80, v2
	v_mov_b32_e32 v81, v2
	v_mov_b32_e32 v90, v2
	v_mov_b32_e32 v91, v2
	v_mov_b32_e32 v92, v2
	v_mov_b32_e32 v93, v2
	v_mov_b32_e32 v94, v2
	v_mov_b32_e32 v95, v2
	v_mov_b32_e32 v96, v2
	v_mov_b32_e32 v97, v2
	v_mov_b32_e32 v106, v2
	v_mov_b32_e32 v107, v2
	v_mov_b32_e32 v108, v2
	v_mov_b32_e32 v109, v2
	v_mov_b32_e32 v110, v2
	v_mov_b32_e32 v111, v2
	v_mov_b32_e32 v112, v2
	v_mov_b32_e32 v113, v2
	v_mov_b32_e32 v122, v2
	v_mov_b32_e32 v123, v2
	v_mov_b32_e32 v124, v2
	v_mov_b32_e32 v125, v2
	v_mov_b32_e32 v126, v2
	v_mov_b32_e32 v127, v2
	v_mov_b32_e32 v128, v2
	v_mov_b32_e32 v129, v2
	s_nop 0
	s_nop 0
	s_nop 0
	s_nop 0
	s_nop 0
